# u2 + dynamic distribution of the last two tile rounds of the up GEMM (global ticket counter, LDS mailbox per workgroup): balances XCD speed differences
# speedup vs baseline: 1.0020x; 1.0020x over previous
; #define LAS __attribute__((address_space(3)))
; __device__ __forceinline__ void xcd_barrier_complete(unsigned* bar, unsigned x, unsigned& nloc, unsigned& nx) {
;     const unsigned G = gridDim.x * gridDim.y * gridDim.z;
; __global__ void __launch_bounds__(NWAVES * 64, 2) fwd_mega(Args args_unused) {
;     extern __shared__ __attribute__((aligned(16))) unsigned char lds_raw[];
;     cg::grid_group grid = cg::this_grid();
;     LAS unsigned char* lds = (LAS unsigned char*)lds_raw;
;     const int wave_s = __builtin_amdgcn_readfirstlane(threadIdx.x >> 6);
;     volatile LAS unsigned* bar_st = (volatile LAS unsigned*)(lds + 131072);
;     if (threadIdx.x < 2) bar_st[threadIdx.x] = 0u;
;     __syncthreads();
;     { const Args* ap0 = (const Args*)__builtin_amdgcn_kernarg_segment_ptr(); (void)xcd_barrier_post((unsigned*)(ap0->ws + WS_CTL), bar_st); }
.LBB0_5:
	s_or_b64 exec, exec, s[4:5]
	s_load_dwordx2 s[4:5], s[0:1], 0x90
	v_lshrrev_b32_e32 v2, 20, v0
	v_lshrrev_b32_e32 v0, 10, v0
	v_or_b32_e32 v0, v0, v2
	s_lshr_b32 s3, s3, 6
	s_mov_b32 s100, 0
	s_nop 0
	v_writelane_b32 v255, s100, 24
	s_waitcnt lgkmcnt(0)
	s_mul_i32 s17, s5, s4
	s_load_dword s4, s[0:1], 0x98
	v_mov_b32_e32 v20, 0
	s_movk_i32 s41, 0x5400
	v_mov_b32_e32 v244, 0x358637bd
	s_mov_b32 s88, 0xf800000
	s_waitcnt lgkmcnt(0)
	s_mul_i32 s17, s17, s4
	s_movk_i32 s4, 0x3ff
	v_and_or_b32 v0, v0, s4, v1
	s_add_i32 s4, 0, 0x20000
	v_writelane_b32 v255, s4, 2
	s_add_i32 s4, 0, 0x20004
	v_writelane_b32 v255, s4, 3
	s_add_i32 s4, 0, 0x3600
	v_writelane_b32 v255, s4, 4
	s_add_i32 s4, 0, 0x21040
	v_writelane_b32 v255, s4, 5
	v_cmp_eq_u32_e64 s[4:5], 0, v0
	v_mbcnt_lo_u32_b32 v1, -1, 0
	v_mov_b32_e32 v245, 0x260
	v_writelane_b32 v255, s4, 6
	s_movk_i32 s89, 0x7fff
	s_mov_b32 s91, 0x800000
	v_mov_b32_e32 v246, 0x1000
	v_mov_b32_e32 v247, 0x2000
	v_mov_b32_e32 v249, 1
	s_mov_b32 s30, 0x10000
	s_movk_i32 s33, 0x1000
	s_mov_b32 s42, 0xb000
	s_movk_i32 s29, 0x2c00
	s_movk_i32 s82, 0xffe0
	s_mov_b32 s83, 0x600000
	s_movk_i32 s13, 0x90
	s_mov_b32 s92, 0x3aa2425
	v_mbcnt_hi_u32_b32 v250, -1, v1
	v_mov_b32_e32 v251, 0x41b17218
	v_mov_b32_e32 v252, 0xf149f2ca
	v_mov_b64_e32 v[214:215], 0x400
	v_mov_b64_e32 v[216:217], 0x3ff
	v_mov_b32_e32 v253, 0xfffff800
	s_add_i32 s93, 0, 0x1d040
	s_add_i32 s86, 0, 0x1d050
	s_mov_b32 s31, 0x400000
	s_mov_b32 s28, 0x80000
	s_mov_b32 s94, 0x200000
	s_add_i32 s36, 0, 0x20040
	v_writelane_b32 v255, s5, 7
	s_mov_b64 s[20:21], 0x1000
	s_mov_b64 s[22:23], 0x80
	s_mov_b32 s40, 0x3e000000
	s_mov_b32 s44, s19
	s_branch .LBB0_8

;     __host__ __device__ bool next(int i, Unit& u) const {
;         const long L = (long)i * G + c; if (L >= nwg) return false;
;         int wgid = (int)L; { const int q = nwg / NXCD, r = nwg % NXCD, xcd = wgid % NXCD, off = wgid / NXCD; wgid = (xcd < r ? xcd * (q + 1) : r * (q + 1) + (xcd - r) * q) + off; }
;         const int nig = wgm * nN, gid = wgid / nig, fm = gid * wgm, gsz = (nM - fm) < wgm ? (nM - fm) : wgm;
;         u.pm = fm + ((wgid % nig) % gsz); u.pn = (wgid % nig) / gsz; if (rev) u.pm = nM - 1 - u.pm; return true;
.LBB0_713:
	s_add_i32 s12, s12, 1
	s_cmp_lt_u32 s12, 20
	s_cbranch_scc1 .Ldq_static
	v_readlane_b32 s98, v255, 24
	s_nop 3
	s_add_i32 s98, s98, 1
	s_nop 0
	v_writelane_b32 v255, s98, 24
	s_or_b32 s98, s98, 0x5eed0000
	v_mov_b32_e32 v2, 0x20010
	s_cmp_lg_u32 s3, 0
	s_cbranch_scc1 .Ldq_poll
	s_load_dwordx2 s[100:101], s[0:1], 0x88
	s_waitcnt lgkmcnt(0)
	s_add_u32 s100, s100, 0x6703840
	s_addc_u32 s101, s101, 0
	v_mov_b32_e32 v3, 1
	s_mov_b64 s[6:7], exec
	s_mov_b64 exec, 1
	s_nop 1
	global_atomic_add v4, v20, v3, s[100:101] sc0
	s_nop 1
	s_mov_b64 exec, s[6:7]
	s_waitcnt vmcnt(0)
	s_nop 1
	v_readfirstlane_b32 s99, v4
	v_mov_b32_e32 v4, s98
	s_nop 3
	v_mov_b32_e32 v5, s99
	ds_write_b64 v2, v[4:5]
	s_waitcnt lgkmcnt(0)
	s_branch .Ldq_have
.Ldq_poll:
	s_mov_b32 s100, 0x100000
.Ldq_spin:
	ds_read_b64 v[4:5], v2
	s_waitcnt lgkmcnt(0)
	v_readfirstlane_b32 s101, v4
	v_readfirstlane_b32 s99, v5
	s_nop 3
	s_cmp_eq_u32 s101, s98
	s_cbranch_scc1 .Ldq_have
	s_sleep 1
	s_sub_u32 s100, s100, 1
	s_cmp_lg_u32 s100, 0
	s_cbranch_scc1 .Ldq_spin
	s_mov_b32 s99, 0xffff
.Ldq_have:
	s_sub_u32 s100, s99, 1536
	s_cmp_ge_u32 s99, 1536
	s_cselect_b32 s99, s100, s99
	s_sub_u32 s100, s99, 768
	s_cmp_ge_u32 s99, 768
	s_cselect_b32 s99, s100, s99
	s_mul_i32 s6, s14, 20
	s_add_u32 s6, s6, s99
	s_mov_b32 s7, 0
	s_branch .Ldq_join
.Ldq_static:
	s_mul_i32 s4, s12, s34
	s_mul_hi_u32 s5, s12, s14
	s_add_i32 s5, s5, s4
	s_mul_i32 s4, s12, s14
	s_add_u32 s6, s4, s18
	s_addc_u32 s7, s5, s35
.Ldq_join:
	v_mov_b64_e32 v[0:1], 0x1600
	v_cmp_lt_i64_e64 s[4:5], s[6:7], v[0:1]
	v_mov_b64_e32 v[0:1], 0x15ff
	v_cmp_gt_i64_e32 vcc, s[6:7], v[0:1]
	s_cbranch_vccnz .LBB0_715
	s_ashr_i32 s7, s6, 31
	s_lshr_b32 s7, s7, 29
	s_add_i32 s7, s6, s7
	s_ashr_i32 s9, s7, 3
	s_and_b32 s7, s7, -8
	s_sub_i32 s6, s6, s7
	s_cmp_lt_i32 s6, 0
	s_movk_i32 s7, 0x2c1
	s_cselect_b32 s7, s7, 0x2c0
	s_mul_i32 s6, s6, s7
	s_add_i32 s6, s6, s9
	s_mul_hi_i32 s7, s6, 0x2e8ba2e9
	s_lshr_b32 s9, s7, 31
	s_ashr_i32 s7, s7, 5
	s_add_i32 s7, s7, s9
	s_lshl_b32 s9, s7, 2
	s_sub_i32 s24, 0x80, s9
	s_min_i32 s24, s24, 4
	s_abs_i32 s25, s24
	v_cvt_f32_u32_e32 v0, s25
	s_sub_i32 s69, 0, s25
	s_mulk_i32 s7, 0xb0
	s_sub_i32 s6, s6, s7
	v_rcp_iflag_f32_e32 v0, v0
	s_abs_i32 s7, s6
	s_xor_b32 s68, s6, s24
	s_ashr_i32 s68, s68, 31
	v_mul_f32_e32 v0, 0x4f7ffffe, v0
	v_cvt_u32_f32_e32 v0, v0
	s_nop 0
	v_readfirstlane_b32 s70, v0
	s_mul_i32 s69, s69, s70
	s_mul_hi_u32 s69, s70, s69
	s_add_i32 s70, s70, s69
	s_mul_hi_u32 s69, s7, s70
	s_mul_i32 s70, s69, s25
	s_sub_i32 s7, s7, s70
	s_add_i32 s71, s69, 1
	s_sub_i32 s70, s7, s25
	s_cmp_ge_u32 s7, s25
	s_cselect_b32 s69, s71, s69
	s_cselect_b32 s7, s70, s7
	s_add_i32 s70, s69, 1
	s_cmp_ge_u32 s7, s25
	s_cselect_b32 s7, s70, s69
	s_xor_b32 s7, s7, s68
	s_sub_i32 s68, s7, s68
	s_mul_i32 s7, s68, s24
	s_sub_i32 s6, s6, s7
	s_add_i32 s70, s9, s6
